# MLA: running-max shift folded into the QK accumulator (C operand block) - 32 v_sub per key tile removed; P0 row conversion and rstd-scaled epilogues: loads issued in batches behind counted waits inste
# speedup vs baseline: 1.0239x; 1.0239x over previous
; DI u32x2 pk4(float a, float b, float c, float d) { u32x2 r; r.x = pk2(a, b); r.y = pk2(c, d); return r; }
; DI void phase0(const Params& p, unsigned char* smem, int tid) {
;     ...
;         for (int t = gw; t < TP; t += nw) {
;             if (t < T) {
;                 const int b = t / L, l = t - b * L;
;                 const float* src = (l < NMETA) ? (p.meta + (size_t)l * D) : (p.x + ((size_t)b * S + (l - NMETA)) * D);
;                 float ss = 0.f;
; #pragma unroll
;                 for (int c = 0; c < 4; ++c) {
;                     f32x4 v = __builtin_nontemporal_load((const f32x4*)(src + (c * 64 + lane) * 4));
;                     ss += v[0] * v[0] + v[1] * v[1] + v[2] * v[2] + v[3] * v[3];
;                     *(u32x2*)(hb + (size_t)t * D + (c * 64 + lane) * 4) = pk4(v[0], v[1], v[2], v[3]);
;                 }
; #pragma unroll
;                 for (int o = 32; o > 0; o >>= 1) ss += __shfl_xor(ss, o);
;                 if (lane == 0) rstd[t] = 1.0f / sqrtf(ss * (1.0f / D) + EPS);
.LBB0_57:
	v_mul_hi_i32 v10, v6, s16
	v_lshrrev_b32_e32 v11, 31, v10
	v_ashrrev_i32_e32 v10, 11, v10
	v_add_u32_e32 v14, v10, v11
	v_mad_i32_i24 v10, v14, s17, v6
	v_cmp_lt_i32_e32 vcc, 15, v10
	s_waitcnt lgkmcnt(0)
	v_mov_b64_e32 v[12:13], s[10:11]
	s_and_saveexec_b64 s[6:7], vcc
	s_xor_b64 s[6:7], exec, s[6:7]
	v_ashrrev_i32_e32 v15, 31, v14
	v_lshlrev_b64 v[12:13], 24, v[14:15]
	v_add_u32_e32 v10, -16, v10
	v_mov_b32_e32 v11, v3
	v_lshl_add_u64 v[12:13], s[8:9], 0, v[12:13]
	s_andn2_saveexec_b64 s[6:7], s[6:7]
	v_ashrrev_i32_e32 v11, 31, v10
	s_or_b64 exec, exec, s[6:7]
	v_lshlrev_b64 v[10:11], 12, v[10:11]
	v_lshl_add_u64 v[10:11], v[12:13], 0, v[10:11]
	v_lshl_add_u64 v[14:15], v[10:11], 0, v[2:3]
	global_load_dwordx4 v[10:13], v[14:15], off nt
	global_load_dwordx4 v[26:29], v[14:15], off offset:1024 nt
	global_load_dwordx4 v[30:33], v[14:15], off offset:2048 nt
	global_load_dwordx4 v[34:37], v[14:15], off offset:3072 nt
	v_cmp_lt_i32_e32 vcc, v19, v18
	s_mov_b64 s[6:7], s[28:29]
	s_waitcnt vmcnt(3)
	v_cvt_pk_bf16_f32 v38, v10, v11
	v_cvt_pk_bf16_f32 v39, v12, v13
	global_store_dwordx2 v[8:9], v[38:39], off offset:-1024
	v_mul_f32_e32 v11, v11, v11
	v_fmac_f32_e32 v11, v10, v10
	v_fmac_f32_e32 v11, v12, v12
	v_fmac_f32_e32 v11, v13, v13
	s_waitcnt vmcnt(3)
	v_cvt_pk_bf16_f32 v40, v26, v27
	v_cvt_pk_bf16_f32 v41, v28, v29
	global_store_dwordx2 v[8:9], v[40:41], off offset:-512
	v_mul_f32_e32 v10, v27, v27
	v_fmac_f32_e32 v10, v26, v26
	v_fmac_f32_e32 v10, v28, v28
	v_fmac_f32_e32 v10, v29, v29
	v_add_f32_e32 v10, v11, v10
	s_waitcnt vmcnt(3)
	v_cvt_pk_bf16_f32 v42, v30, v31
	v_cvt_pk_bf16_f32 v43, v32, v33
	global_store_dwordx2 v[8:9], v[42:43], off
	v_mul_f32_e32 v11, v31, v31
	v_fmac_f32_e32 v11, v30, v30
	v_fmac_f32_e32 v11, v32, v32
	v_fmac_f32_e32 v11, v33, v33
	v_add_f32_e32 v10, v10, v11
	v_cndmask_b32_e32 v14, v17, v19, vcc
	v_lshlrev_b32_e32 v14, 2, v14
	v_cmp_lt_i32_e32 vcc, v20, v18
	s_waitcnt vmcnt(3)
	v_mul_f32_e32 v11, v35, v35
	v_fmac_f32_e32 v11, v34, v34
	v_fmac_f32_e32 v11, v36, v36
	v_fmac_f32_e32 v11, v37, v37
	v_add_f32_e32 v10, v10, v11
	ds_bpermute_b32 v11, v14, v10
	v_cndmask_b32_e32 v12, v17, v20, vcc
	v_lshlrev_b32_e32 v12, 2, v12
	v_cmp_lt_i32_e32 vcc, v21, v18
	v_cvt_pk_bf16_f32 v13, v36, v37
	s_waitcnt lgkmcnt(0)
	v_add_f32_e32 v10, v10, v11
	ds_bpermute_b32 v11, v12, v10
	v_cndmask_b32_e32 v12, v17, v21, vcc
	v_lshlrev_b32_e32 v12, 2, v12
	v_cmp_lt_i32_e32 vcc, v22, v18
	s_waitcnt lgkmcnt(0)
	v_add_f32_e32 v10, v10, v11
	ds_bpermute_b32 v11, v12, v10
	v_cndmask_b32_e32 v12, v17, v22, vcc
	v_lshlrev_b32_e32 v12, 2, v12
	v_cmp_lt_i32_e32 vcc, v23, v18
	s_waitcnt lgkmcnt(0)
	v_add_f32_e32 v10, v10, v11
	ds_bpermute_b32 v11, v12, v10
	v_cndmask_b32_e32 v12, v17, v23, vcc
	v_lshlrev_b32_e32 v12, 2, v12
	v_cmp_lt_i32_e32 vcc, v24, v18
	s_waitcnt lgkmcnt(0)
	v_add_f32_e32 v10, v10, v11
	ds_bpermute_b32 v11, v12, v10
	v_cndmask_b32_e32 v12, v17, v24, vcc
	s_waitcnt lgkmcnt(0)
	v_add_f32_e32 v10, v10, v11
	v_lshlrev_b32_e32 v11, 2, v12
	ds_bpermute_b32 v11, v11, v10
	v_cvt_pk_bf16_f32 v12, v34, v35
	global_store_dwordx2 v[8:9], v[12:13], off offset:512
	s_and_saveexec_b64 s[34:35], s[4:5]
	s_cbranch_execz .LBB0_63
	s_waitcnt lgkmcnt(0)
	v_add_f32_e32 v10, v10, v11
	v_fmamk_f32 v10, v10, 0x3a800000, v1
	v_mul_f32_e32 v11, 0x4f800000, v10
	v_cmp_gt_f32_e32 vcc, s33, v10
	s_nop 1
	v_cndmask_b32_e32 v10, v10, v11, vcc
	v_sqrt_f32_e32 v11, v10
	s_nop 0
	v_add_u32_e32 v12, -1, v11
	v_fma_f32 v14, -v12, v11, v10
	v_add_u32_e32 v13, 1, v11
	v_cmp_ge_f32_e64 s[6:7], 0, v14
	s_nop 1
	v_cndmask_b32_e64 v12, v11, v12, s[6:7]
	v_fma_f32 v11, -v13, v11, v10
	v_cmp_lt_f32_e64 s[6:7], 0, v11
	s_nop 1
	v_cndmask_b32_e64 v11, v12, v13, s[6:7]
	v_mul_f32_e32 v12, 0x37800000, v11
	v_cndmask_b32_e32 v11, v11, v12, vcc
	v_cmp_class_f32_e32 vcc, v10, v16
	s_nop 1
	v_cndmask_b32_e32 v10, v11, v10, vcc
	v_div_scale_f32 v11, s[6:7], v10, v10, 1.0
	v_rcp_f32_e32 v12, v11
	s_or_b64 s[6:7], s[28:29], exec
	v_fma_f32 v13, -v11, v12, 1.0
	v_fmac_f32_e32 v12, v13, v12
	v_div_scale_f32 v13, vcc, 1.0, v10, 1.0
	v_mul_f32_e32 v14, v13, v12
	v_fma_f32 v15, -v11, v14, v13
	v_fmac_f32_e32 v14, v15, v12
	v_fma_f32 v11, -v11, v14, v13
	v_div_fmas_f32 v11, v11, v12, v14
	v_div_fixup_f32 v12, v11, v10, 1.0

; #define G_HALF(pl, ql, ps, qs, kt_) { const int k4_ = min((kt_) + 4, nk - 1); \
;         SB G_LOAD(pl, ql, k4_) F_LOAD(fa1, fb1, cur, 1) SB G_MFMA(fa0, fb0) SB G_STORE(ps, qs, wr) F_LOAD(fa0, fb0, nxt, 0) SB G_MFMA(fa1, fb1) SB \
;         __syncthreads(); { const int t_ = cur; cur = nxt; nxt = wr; wr = t_; } }
; #define G_HALF(pl, ql, ps, qs, kt_) { const int k4_ = min((kt_) + 4, nk - 1); \
;         SB R_BURST1(fb0, fb1, cur, 1, pl, ql, k4_, ps, qs, wr) R_BURST2(fb1, fb0, nxt, 0, ps, qs, wr) \
;         __syncthreads(); { const int t_ = cur; cur = nxt; nxt = wr; wr = t_; } }
; #define G_HALF(pl, ql, ps, qs, kt_) { const int k4_ = min((kt_) + 4, nk - 1); \
;         SB R_BURST1(fb0, fb1, cur, 1, pl, ql, k4_, ps, qs, wr) R_BURST2(fb1, fb0, nxt, 0, ps, qs, wr) \
;         __syncthreads(); { const int t_ = cur; cur = nxt; nxt = wr; wr = t_; } }
;     ...
; #pragma unroll 1
;     for (; kt + 3 <= nk; kt += 3) {
;         G_HALF(p1, q1, p2, q2, kt)
;         G_HALF(p2, q2, p0, q0, kt + 1)
;         G_HALF(p0, q0, p1, q1, kt + 2)
;     }
.LBB0_218:
	s_waitcnt lgkmcnt(1)
	s_nop 0
	v_mfma_f32_32x32x16_bf16 v[112:127], v[144:147], v[184:187], v[112:127]
	ds_read_b128 v[220:223], v204 offset:22560
	s_waitcnt vmcnt(7)
	ds_write_b128 v196, v[172:175]
	s_waitcnt lgkmcnt(2)
	v_mfma_f32_32x32x16_bf16 v[48:63], v[144:147], v[128:131], v[48:63]
	ds_read_b128 v[172:175], v211 offset:2080
	global_load_dwordx4 v[144:147], v250, s[98:99] offset:256
	v_mfma_f32_32x32x16_bf16 v[96:111], v[140:143], v[184:187], v[96:111]
	ds_read_b128 v[224:227], v204 offset:25120
	s_waitcnt vmcnt(6)
	ds_write_b128 v195, v[180:183]
	v_mfma_f32_32x32x16_bf16 v[32:47], v[140:143], v[128:131], v[32:47]
	ds_read_b128 v[180:183], v211 offset:4640
	global_load_dwordx4 v[140:143], v251, s[98:99] offset:256
	v_mfma_f32_32x32x16_bf16 v[80:95], v[136:139], v[184:187], v[80:95]
	s_waitcnt vmcnt(5)
	ds_write_b128 v193, v[168:171]
	v_mfma_f32_32x32x16_bf16 v[16:31], v[136:139], v[128:131], v[16:31]
	ds_read_b128 v[168:171], v211 offset:7200
	global_load_dwordx4 v[136:139], v250, s[100:101] offset:256
	v_mfma_f32_32x32x16_bf16 v[64:79], v[132:135], v[184:187], v[64:79]
	s_waitcnt vmcnt(4)
	ds_write_b128 v192, v[164:167]
	v_mfma_f32_32x32x16_bf16 v[0:15], v[132:135], v[128:131], v[0:15]
	ds_read_b128 v[132:135], v211 offset:9760
	global_load_dwordx4 v[128:131], v251, s[100:101] offset:256
	s_waitcnt lgkmcnt(7)
	v_mfma_f32_32x32x16_bf16 v[112:127], v[172:175], v[220:223], v[112:127]
	ds_read_b128 v[164:167], v204 offset:63488
	s_waitcnt lgkmcnt(7)
	v_mfma_f32_32x32x16_bf16 v[48:63], v[172:175], v[224:227], v[48:63]
	ds_read_b128 v[172:175], v211 offset:43008
	s_waitcnt lgkmcnt(6)
	v_mfma_f32_32x32x16_bf16 v[96:111], v[180:183], v[220:223], v[96:111]
	ds_read_b128 v[184:187], v205 offset:43520
	v_mfma_f32_32x32x16_bf16 v[32:47], v[180:183], v[224:227], v[32:47]
	ds_read_b128 v[180:183], v211 offset:45568
	s_waitcnt lgkmcnt(6)
	v_mfma_f32_32x32x16_bf16 v[80:95], v[168:171], v[220:223], v[80:95]
	v_mfma_f32_32x32x16_bf16 v[16:31], v[168:171], v[224:227], v[16:31]
	ds_read_b128 v[168:171], v211 offset:48128
	s_waitcnt lgkmcnt(5)
	v_mfma_f32_32x32x16_bf16 v[64:79], v[132:135], v[220:223], v[64:79]
	v_mfma_f32_32x32x16_bf16 v[0:15], v[132:135], v[224:227], v[0:15]
	ds_read_b128 v[132:135], v211 offset:50688
	s_waitcnt lgkmcnt(0)
	s_barrier
	v_mfma_f32_32x32x16_bf16 v[112:127], v[172:175], v[164:167], v[112:127]
	ds_read_b128 v[220:223], v204 offset:63520
	ds_write_b128 v210, v[160:163] offset:2048
	v_mfma_f32_32x32x16_bf16 v[48:63], v[172:175], v[184:187], v[48:63]
	global_load_dwordx4 v[172:175], v250, s[98:99] offset:320
	ds_read_b128 v[160:163], v211 offset:43040
	v_mfma_f32_32x32x16_bf16 v[96:111], v[180:183], v[164:167], v[96:111]
	ds_read_b128 v[224:227], v205 offset:43552
	ds_write_b128 v210, v[156:159] offset:12288
	v_mfma_f32_32x32x16_bf16 v[32:47], v[180:183], v[184:187], v[32:47]
	global_load_dwordx4 v[180:183], v251, s[98:99] offset:320
	ds_read_b128 v[156:159], v211 offset:45600
	v_mfma_f32_32x32x16_bf16 v[80:95], v[168:171], v[164:167], v[80:95]
	ds_write_b128 v210, v[148:151] offset:22528
	v_mfma_f32_32x32x16_bf16 v[16:31], v[168:171], v[184:187], v[16:31]
	global_load_dwordx4 v[168:171], v250, s[100:101] offset:320
	ds_read_b128 v[148:151], v211 offset:48160
	v_mfma_f32_32x32x16_bf16 v[64:79], v[132:135], v[164:167], v[64:79]
	s_waitcnt vmcnt(7)
	ds_write_b128 v210, v[152:155] offset:32768
	v_mfma_f32_32x32x16_bf16 v[0:15], v[132:135], v[184:187], v[0:15]
	global_load_dwordx4 v[164:167], v251, s[100:101] offset:320
	ds_read_b128 v[132:135], v211 offset:50720
	s_waitcnt lgkmcnt(7)
	v_mfma_f32_32x32x16_bf16 v[112:127], v[160:163], v[220:223], v[112:127]
	ds_read_b128 v[152:155], v201
	s_waitcnt lgkmcnt(7)
	v_mfma_f32_32x32x16_bf16 v[48:63], v[160:163], v[224:227], v[48:63]
	ds_read_b128 v[160:163], v197
	s_waitcnt lgkmcnt(6)
	v_mfma_f32_32x32x16_bf16 v[96:111], v[156:159], v[220:223], v[96:111]
	ds_read_b128 v[184:187], v202
	v_mfma_f32_32x32x16_bf16 v[32:47], v[156:159], v[224:227], v[32:47]
	ds_read_b128 v[156:159], v198
	s_waitcnt lgkmcnt(6)
	v_mfma_f32_32x32x16_bf16 v[80:95], v[148:151], v[220:223], v[80:95]
	v_mfma_f32_32x32x16_bf16 v[16:31], v[148:151], v[224:227], v[16:31]
	ds_read_b128 v[148:151], v199
	s_waitcnt lgkmcnt(5)
	v_mfma_f32_32x32x16_bf16 v[64:79], v[132:135], v[220:223], v[64:79]
	v_mfma_f32_32x32x16_bf16 v[0:15], v[132:135], v[224:227], v[0:15]
	ds_read_b128 v[132:135], v200
	s_waitcnt lgkmcnt(0)
	s_barrier
	v_mfma_f32_32x32x16_bf16 v[112:127], v[160:163], v[152:155], v[112:127]
	ds_read_b128 v[220:223], v203
	s_waitcnt vmcnt(7)
	ds_write_b128 v210, v[144:147] offset:43008
	v_mfma_f32_32x32x16_bf16 v[48:63], v[160:163], v[184:187], v[48:63]
	global_load_dwordx4 v[160:163], v250, s[98:99] offset:384
	ds_read_b128 v[144:147], v206
	v_mfma_f32_32x32x16_bf16 v[96:111], v[156:159], v[152:155], v[96:111]
	ds_read_b128 v[224:227], v207
	s_waitcnt vmcnt(7)
	ds_write_b128 v210, v[140:143] offset:53248
	v_mfma_f32_32x32x16_bf16 v[32:47], v[156:159], v[184:187], v[32:47]
	global_load_dwordx4 v[156:159], v251, s[98:99] offset:384
	ds_read_b128 v[140:143], v216
	v_mfma_f32_32x32x16_bf16 v[80:95], v[148:151], v[152:155], v[80:95]
	s_waitcnt vmcnt(7)
	ds_write_b128 v210, v[136:139] offset:63488
	v_mfma_f32_32x32x16_bf16 v[16:31], v[148:151], v[184:187], v[16:31]
	global_load_dwordx4 v[148:151], v250, s[100:101] offset:384
	ds_read_b128 v[136:139], v217
	v_mfma_f32_32x32x16_bf16 v[64:79], v[132:135], v[152:155], v[64:79]
	s_waitcnt vmcnt(7)
	ds_write_b128 v194, v[128:131]
	v_mfma_f32_32x32x16_bf16 v[0:15], v[132:135], v[184:187], v[0:15]
	ds_read_b128 v[132:135], v218
	global_load_dwordx4 v[152:155], v251, s[100:101] offset:384
	s_waitcnt lgkmcnt(7)
	v_mfma_f32_32x32x16_bf16 v[112:127], v[144:147], v[220:223], v[112:127]
	ds_read_b128 v[184:187], v204 offset:22528
	s_waitcnt lgkmcnt(7)
	v_mfma_f32_32x32x16_bf16 v[48:63], v[144:147], v[224:227], v[48:63]
	ds_read_b128 v[144:147], v211 offset:2048
	s_waitcnt lgkmcnt(6)
	v_mfma_f32_32x32x16_bf16 v[96:111], v[140:143], v[220:223], v[96:111]
	ds_read_b128 v[128:131], v204 offset:25088
	v_mfma_f32_32x32x16_bf16 v[32:47], v[140:143], v[224:227], v[32:47]
	ds_read_b128 v[140:143], v211 offset:4608
	s_waitcnt lgkmcnt(6)
	v_mfma_f32_32x32x16_bf16 v[80:95], v[136:139], v[220:223], v[80:95]
	v_mfma_f32_32x32x16_bf16 v[16:31], v[136:139], v[224:227], v[16:31]
	ds_read_b128 v[136:139], v211 offset:7168
	s_waitcnt lgkmcnt(5)
	v_mfma_f32_32x32x16_bf16 v[64:79], v[132:135], v[220:223], v[64:79]
	v_mfma_f32_32x32x16_bf16 v[0:15], v[132:135], v[224:227], v[0:15]
	ds_read_b128 v[132:135], v211 offset:9728
	s_add_i32 s5, s5, 3
	v_add_u32_e32 v250, 0xc0, v250
	s_cmp_lt_u32 s5, 30
	v_add_u32_e32 v251, 0xc0, v251
	s_waitcnt lgkmcnt(0)
	s_barrier
; #define G_HALF(pl, ql, ps, qs, kt_) { const int k4_ = min((kt_) + 4, nk - 1); \
;         SB G_LOAD(pl, ql, k4_) F_LOAD(fa1, fb1, cur, 1) SB G_MFMA(fa0, fb0) SB G_STORE(ps, qs, wr) F_LOAD(fa0, fb0, nxt, 0) SB G_MFMA(fa1, fb1) SB \
;         __syncthreads(); { const int t_ = cur; cur = nxt; nxt = wr; wr = t_; } }
; #define G_HALF(pl, ql, ps, qs, kt_) { const int k4_ = min((kt_) + 4, nk - 1); \
;         SB R_BURST1(fb0, fb1, cur, 1, pl, ql, k4_, ps, qs, wr) R_BURST2(fb1, fb0, nxt, 0, ps, qs, wr) \
;         __syncthreads(); { const int t_ = cur; cur = nxt; nxt = wr; wr = t_; } }
; #define G_HALF(pl, ql, ps, qs, kt_) { const int k4_ = min((kt_) + 4, nk - 1); \
;         SB R_BURST1(fb0, fb1, cur, 1, pl, ql, k4_, ps, qs, wr) R_BURST2(fb1, fb0, nxt, 0, ps, qs, wr) \
;         __syncthreads(); { const int t_ = cur; cur = nxt; nxt = wr; wr = t_; } }
;     ...
;     if (kt < nk) G_HALF(p1, q1, p2, q2, kt)
;     if (kt + 1 < nk) G_HALF(p2, q2, p0, q0, kt + 1)
	s_cbranch_scc1 .LBB0_218
	s_add_i32 s5, s8, 0xfffff700
	v_mfma_f32_32x32x16_bf16 v[112:127], v[144:147], v[184:187], v[112:127]
	ds_read_b128 v[200:203], v204 offset:22560
	s_waitcnt vmcnt(7)
	ds_write_b128 v196, v[172:175]
	ds_read_b128 v[172:175], v211 offset:2080
	v_mfma_f32_32x32x16_bf16 v[96:111], v[140:143], v[184:187], v[96:111]
	ds_read_b128 v[176:179], v204 offset:25120
	s_waitcnt vmcnt(6)
	ds_write_b128 v195, v[180:183]
	ds_read_b128 v[180:183], v211 offset:4640
	v_mfma_f32_32x32x16_bf16 v[80:95], v[136:139], v[184:187], v[80:95]
	s_waitcnt vmcnt(5)
	ds_write_b128 v193, v[168:171]
	ds_read_b128 v[168:171], v211 offset:7200
	v_mfma_f32_32x32x16_bf16 v[64:79], v[132:135], v[184:187], v[64:79]
	s_waitcnt vmcnt(4)
	ds_write_b128 v192, v[164:167]
	ds_read_b128 v[164:167], v211 offset:9760
	s_waitcnt lgkmcnt(7)
	v_mfma_f32_32x32x16_bf16 v[112:127], v[172:175], v[200:203], v[112:127]
	ds_read_b128 v[216:219], v204 offset:63488
	ds_read_b128 v[184:187], v211 offset:43008
	s_waitcnt lgkmcnt(6)
	v_mfma_f32_32x32x16_bf16 v[96:111], v[180:183], v[200:203], v[96:111]
	ds_read_b128 v[188:191], v205 offset:43520
	ds_read_b128 v[192:195], v211 offset:45568
	s_waitcnt lgkmcnt(6)
	v_mfma_f32_32x32x16_bf16 v[80:95], v[168:171], v[200:203], v[80:95]
	ds_read_b128 v[196:199], v211 offset:48128
	s_waitcnt lgkmcnt(5)
	v_mfma_f32_32x32x16_bf16 v[64:79], v[164:167], v[200:203], v[64:79]
	ds_read_b128 v[200:203], v211 offset:50688
	s_waitcnt lgkmcnt(0)
	s_barrier
	v_mfma_f32_32x32x16_bf16 v[112:127], v[184:187], v[216:219], v[112:127]
	ds_read_b128 v[220:223], v204 offset:63520
	s_waitcnt vmcnt(3)
	ds_write_b128 v210, v[160:163] offset:2048
	ds_read_b128 v[160:163], v211 offset:43040
	v_mfma_f32_32x32x16_bf16 v[96:111], v[192:195], v[216:219], v[96:111]
	ds_read_b128 v[204:207], v205 offset:43552
	s_waitcnt vmcnt(2)
	ds_write_b128 v210, v[156:159] offset:12288
	ds_read_b128 v[156:159], v211 offset:45600
	v_mfma_f32_32x32x16_bf16 v[80:95], v[196:199], v[216:219], v[80:95]
	s_waitcnt vmcnt(1)
	ds_write_b128 v210, v[148:151] offset:22528
	ds_read_b128 v[148:151], v211 offset:48160
	v_mfma_f32_32x32x16_bf16 v[64:79], v[200:203], v[216:219], v[64:79]
	s_waitcnt vmcnt(0)
	ds_write_b128 v210, v[152:155] offset:32768
	ds_read_b128 v[152:155], v211 offset:50720
	s_waitcnt lgkmcnt(7)
	v_mfma_f32_32x32x16_bf16 v[112:127], v[160:163], v[220:223], v[112:127]
	s_waitcnt lgkmcnt(4)
	v_mfma_f32_32x32x16_bf16 v[96:111], v[156:159], v[220:223], v[96:111]
	s_waitcnt lgkmcnt(2)
	v_mfma_f32_32x32x16_bf16 v[80:95], v[148:151], v[220:223], v[80:95]
	s_waitcnt lgkmcnt(0)
	v_mfma_f32_32x32x16_bf16 v[64:79], v[152:155], v[220:223], v[64:79]
	v_mov_b32_e32 v216, v212
	s_barrier
; DI u32x2 pk4(float a, float b, float c, float d) { u32x2 r; r.x = pk2(a, b); r.y = pk2(c, d); return r; }
; template <int WI, int WGJ, class GetF, class FinF>
; DI void staged_rows(unsigned char* lds, int tid, GetF get, FinF fin) {
;     ...
;     for (int jt = 0; jt < 2; ++jt) {
;         unsigned char* wrow = lds + (wj * 32 + ln) * RS + (wi * WI * 32 + 4 * h) * 2;
; #pragma unroll
;         for (int it = 0; it < WI; ++it)
; #pragma unroll
;             for (int g = 0; g < 4; ++g) *(u32x2*)(wrow + (it * 32 + 8 * g) * 2) = get(it, jt, g);
;         __syncthreads();
; template <int MODE>
; DI void phase1(const Params& p, unsigned char* smem, int tid) {
;     ...
;                 [&](int it, int jt, int g) { const f32x4 rs = *(const f32x4*)(rstd + tt * 256 + wi * 128 + it * 32 + 8 * g + 4 * h);
;                     return pk4(acc[it][jt][4 * g] * rs[0], acc[it][jt][4 * g + 1] * rs[1], acc[it][jt][4 * g + 2] * rs[2], acc[it][jt][4 * g + 3] * rs[3]); },
	s_lshl_b32 s10, s4, 8
	v_ashrrev_i32_e32 v208, 6, v216
	v_lshrrev_b32_e32 v210, 30, v208
	v_add_u32_e32 v210, v208, v210
	v_and_b32_e32 v211, 0x7ffffc, v210
	v_sub_u32_e32 v208, v208, v211
	v_and_b32_e32 v211, 31, v216
	v_lshl_or_b32 v208, v208, 5, v211
	v_lshlrev_b32_e32 v210, 6, v210
	v_mul_lo_u32 v208, v208, s50
	v_and_b32_e32 v210, 0xffffff00, v210
	v_lshrrev_b32_e32 v211, 2, v216
	v_and_b32_e32 v211, 8, v211
	v_add3_u32 v208, 0, v208, v210
	s_ashr_i32 s11, s10, 31
	v_add_u32_e32 v217, v208, v211
	s_lshl_b64 s[12:13], s[10:11], 2
	v_ashrrev_i32_e32 v208, 1, v216
	s_add_u32 s12, s40, s12
	v_and_b32_e32 v210, 0xffffff80, v208
	s_addc_u32 s13, s41, s13
	v_ashrrev_i32_e32 v211, 31, v210
	v_lshrrev_b32_e32 v208, 1, v216
	v_lshl_add_u64 v[210:211], v[210:211], 2, s[12:13]
	v_and_b32_e32 v208, 16, v208
	v_lshl_add_u64 v[210:211], v[210:211], 0, v[208:209]
	global_load_dwordx4 v[222:225], v[210:211], off
	global_load_dwordx4 v[226:229], v[210:211], off offset:32
	global_load_dwordx4 v[230:233], v[210:211], off offset:64
	global_load_dwordx4 v[234:237], v[210:211], off offset:96
	global_load_dwordx4 v[238:241], v[210:211], off offset:128
	global_load_dwordx4 v[242:245], v[210:211], off offset:160
	global_load_dwordx4 v[248:251], v[210:211], off offset:192
	global_load_dwordx4 v[252:255], v[210:211], off offset:224
	s_mov_b32 s9, 0
	s_waitcnt vmcnt(7)
	v_pk_mul_f32 v[112:113], v[112:113], v[222:223]
	v_pk_mul_f32 v[114:115], v[114:115], v[224:225]
	v_cvt_pk_bf16_f32 v218, v112, v113
	v_cvt_pk_bf16_f32 v219, v114, v115
	s_waitcnt vmcnt(6)
	v_pk_mul_f32 v[112:113], v[116:117], v[226:227]
	v_pk_mul_f32 v[114:115], v[118:119], v[228:229]
	v_cvt_pk_bf16_f32 v116, v112, v113
	v_cvt_pk_bf16_f32 v117, v114, v115
	v_add_u32_e32 v112, 0x800, v217
	ds_write2_b64 v112, v[218:219], v[116:117] offset1:2
	s_waitcnt vmcnt(5)
	v_pk_mul_f32 v[114:115], v[120:121], v[230:231]
	v_pk_mul_f32 v[116:117], v[122:123], v[232:233]
	v_cvt_pk_bf16_f32 v118, v114, v115
	v_cvt_pk_bf16_f32 v119, v116, v117
	s_waitcnt vmcnt(4)
	v_pk_mul_f32 v[114:115], v[124:125], v[234:235]
	v_pk_mul_f32 v[116:117], v[126:127], v[236:237]
	v_cvt_pk_bf16_f32 v114, v114, v115
	v_cvt_pk_bf16_f32 v115, v116, v117
	ds_write2_b64 v112, v[118:119], v[114:115] offset0:4 offset1:6
	s_waitcnt vmcnt(3)
	v_pk_mul_f32 v[96:97], v[96:97], v[238:239]
	v_pk_mul_f32 v[98:99], v[98:99], v[240:241]
	v_cvt_pk_bf16_f32 v114, v96, v97
	v_cvt_pk_bf16_f32 v115, v98, v99
	s_waitcnt vmcnt(2)
	v_pk_mul_f32 v[96:97], v[100:101], v[242:243]
	v_pk_mul_f32 v[98:99], v[102:103], v[244:245]
	v_cvt_pk_bf16_f32 v96, v96, v97
	v_cvt_pk_bf16_f32 v97, v98, v99
	ds_write2_b64 v112, v[114:115], v[96:97] offset0:8 offset1:10
	s_waitcnt vmcnt(1)
	v_pk_mul_f32 v[96:97], v[104:105], v[248:249]
	v_pk_mul_f32 v[98:99], v[106:107], v[250:251]
	v_cvt_pk_bf16_f32 v100, v96, v97
	v_cvt_pk_bf16_f32 v101, v98, v99
	s_waitcnt vmcnt(0)
	v_pk_mul_f32 v[96:97], v[108:109], v[252:253]
	v_pk_mul_f32 v[98:99], v[110:111], v[254:255]
	v_cvt_pk_bf16_f32 v96, v96, v97
	v_cvt_pk_bf16_f32 v97, v98, v99
	ds_write2_b64 v112, v[100:101], v[96:97] offset0:12 offset1:14
	global_load_dwordx4 v[222:225], v[210:211], off offset:256
	global_load_dwordx4 v[226:229], v[210:211], off offset:288
	global_load_dwordx4 v[230:233], v[210:211], off offset:320
	global_load_dwordx4 v[234:237], v[210:211], off offset:352
	global_load_dwordx4 v[238:241], v[210:211], off offset:384
	global_load_dwordx4 v[242:245], v[210:211], off offset:416
	global_load_dwordx4 v[248:251], v[210:211], off offset:448
	global_load_dwordx4 v[252:255], v[210:211], off offset:480
	s_waitcnt vmcnt(7)
	v_pk_mul_f32 v[80:81], v[80:81], v[222:223]
	v_pk_mul_f32 v[82:83], v[82:83], v[224:225]
	v_cvt_pk_bf16_f32 v96, v80, v81
	v_cvt_pk_bf16_f32 v97, v82, v83
	s_waitcnt vmcnt(6)
	v_pk_mul_f32 v[80:81], v[84:85], v[226:227]
	v_pk_mul_f32 v[82:83], v[86:87], v[228:229]
	v_cvt_pk_bf16_f32 v80, v80, v81
	v_cvt_pk_bf16_f32 v81, v82, v83
	ds_write2_b64 v112, v[96:97], v[80:81] offset0:16 offset1:18
	s_waitcnt vmcnt(5)
	v_pk_mul_f32 v[80:81], v[88:89], v[230:231]
	v_pk_mul_f32 v[82:83], v[90:91], v[232:233]
	v_cvt_pk_bf16_f32 v84, v80, v81
	v_cvt_pk_bf16_f32 v85, v82, v83
	s_waitcnt vmcnt(4)
	v_pk_mul_f32 v[80:81], v[92:93], v[234:235]
	v_pk_mul_f32 v[82:83], v[94:95], v[236:237]
	v_cvt_pk_bf16_f32 v80, v80, v81
	v_cvt_pk_bf16_f32 v81, v82, v83
	ds_write2_b64 v112, v[84:85], v[80:81] offset0:20 offset1:22
	s_waitcnt vmcnt(3)
	v_pk_mul_f32 v[64:65], v[64:65], v[238:239]
	v_pk_mul_f32 v[66:67], v[66:67], v[240:241]
	v_cvt_pk_bf16_f32 v80, v64, v65
	v_cvt_pk_bf16_f32 v81, v66, v67
	s_waitcnt vmcnt(2)
	v_pk_mul_f32 v[64:65], v[68:69], v[242:243]
	v_pk_mul_f32 v[66:67], v[70:71], v[244:245]
	v_cvt_pk_bf16_f32 v64, v64, v65
	v_cvt_pk_bf16_f32 v65, v66, v67
	ds_write2_b64 v112, v[80:81], v[64:65] offset0:24 offset1:26
	s_waitcnt vmcnt(1)
	v_pk_mul_f32 v[64:65], v[72:73], v[248:249]
	v_pk_mul_f32 v[66:67], v[74:75], v[250:251]
	v_cvt_pk_bf16_f32 v68, v64, v65
	v_cvt_pk_bf16_f32 v69, v66, v67
	s_waitcnt vmcnt(0)
	v_pk_mul_f32 v[64:65], v[76:77], v[252:253]
	v_pk_mul_f32 v[66:67], v[78:79], v[254:255]
	v_cvt_pk_bf16_f32 v64, v64, v65
	v_cvt_pk_bf16_f32 v65, v66, v67
	ds_write2_b64 v112, v[68:69], v[64:65] offset0:28 offset1:30
	s_waitcnt lgkmcnt(0)
	s_barrier
	s_branch .LBB0_221

; DI u32x2 pk4(float a, float b, float c, float d) { u32x2 r; r.x = pk2(a, b); r.y = pk2(c, d); return r; }
; template <int WI, int WGJ, class GetF, class FinF>
; DI void staged_rows(unsigned char* lds, int tid, GetF get, FinF fin) {
;     ...
;     for (int jt = 0; jt < 2; ++jt) {
;         unsigned char* wrow = lds + (wj * 32 + ln) * RS + (wi * WI * 32 + 4 * h) * 2;
; #pragma unroll
;         for (int it = 0; it < WI; ++it)
; #pragma unroll
;             for (int g = 0; g < 4; ++g) *(u32x2*)(wrow + (it * 32 + 8 * g) * 2) = get(it, jt, g);
;         __syncthreads();
; template <int MODE>
; DI void phase1(const Params& p, unsigned char* smem, int tid) {
;     ...
;                 [&](int it, int jt, int g) { const f32x4 rs = *(const f32x4*)(rstd + tt * 256 + wi * 128 + it * 32 + 8 * g + 4 * h);
;                     return pk4(acc[it][jt][4 * g] * rs[0], acc[it][jt][4 * g + 1] * rs[1], acc[it][jt][4 * g + 2] * rs[2], acc[it][jt][4 * g + 3] * rs[3]); },
.LBB0_223:
	s_barrier
	global_load_dwordx4 v[222:225], v[210:211], off
	global_load_dwordx4 v[226:229], v[210:211], off offset:32
	global_load_dwordx4 v[230:233], v[210:211], off offset:64
	global_load_dwordx4 v[234:237], v[210:211], off offset:96
	global_load_dwordx4 v[238:241], v[210:211], off offset:128
	global_load_dwordx4 v[242:245], v[210:211], off offset:160
	global_load_dwordx4 v[248:251], v[210:211], off offset:192
	global_load_dwordx4 v[252:255], v[210:211], off offset:224
	v_mfma_f32_32x32x16_bf16 v[48:63], v[144:147], v[128:131], v[48:63]
	s_add_i32 s5, s8, 0xfffff720
	s_mov_b32 s11, 0
	v_mfma_f32_32x32x16_bf16 v[48:63], v[172:175], v[176:179], v[48:63]
	v_mfma_f32_32x32x16_bf16 v[48:63], v[184:187], v[188:191], v[48:63]
	v_mfma_f32_32x32x16_bf16 v[48:63], v[160:163], v[204:207], v[48:63]
	v_mfma_f32_32x32x16_bf16 v[32:47], v[140:143], v[128:131], v[32:47]
	s_waitcnt vmcnt(7)
	s_nop 9
	v_mul_f32_e64 v48, v48, v222
	v_mul_f32_e64 v49, v49, v223
	v_mul_f32_e64 v50, v50, v224
	v_mul_f32_e64 v51, v51, v225
	v_cvt_pk_bf16_f32 v64, v48, v49
	v_cvt_pk_bf16_f32 v65, v50, v51
	v_mfma_f32_32x32x16_bf16 v[32:47], v[180:183], v[176:179], v[32:47]
	s_waitcnt vmcnt(6)
	v_mul_f32_e64 v48, v52, v226
	v_mul_f32_e64 v49, v53, v227
	v_mul_f32_e64 v50, v54, v228
	v_mul_f32_e64 v51, v55, v229
	v_cvt_pk_bf16_f32 v48, v48, v49
	v_cvt_pk_bf16_f32 v49, v50, v51
	ds_write2_b64 v112, v[64:65], v[48:49] offset1:2
	v_mfma_f32_32x32x16_bf16 v[32:47], v[192:195], v[188:191], v[32:47]
	s_waitcnt vmcnt(5)
	v_mul_f32_e64 v48, v56, v230
	v_mul_f32_e64 v49, v57, v231
	v_mul_f32_e64 v50, v58, v232
	v_mul_f32_e64 v51, v59, v233
	v_cvt_pk_bf16_f32 v52, v48, v49
	v_cvt_pk_bf16_f32 v53, v50, v51
	v_mfma_f32_32x32x16_bf16 v[32:47], v[156:159], v[204:207], v[32:47]
	s_waitcnt vmcnt(4)
	v_mul_f32_e64 v48, v60, v234
	v_mul_f32_e64 v49, v61, v235
	v_mul_f32_e64 v50, v62, v236
	v_mul_f32_e64 v51, v63, v237
	v_cvt_pk_bf16_f32 v48, v48, v49
	v_cvt_pk_bf16_f32 v49, v50, v51
	ds_write2_b64 v112, v[52:53], v[48:49] offset0:4 offset1:6
	v_mfma_f32_32x32x16_bf16 v[16:31], v[136:139], v[128:131], v[16:31]
	s_waitcnt vmcnt(3)
	s_nop 0
	v_mul_f32_e64 v32, v32, v238
	v_mul_f32_e64 v33, v33, v239
	v_mul_f32_e64 v34, v34, v240
	v_mul_f32_e64 v35, v35, v241
	v_cvt_pk_bf16_f32 v48, v32, v33
	v_cvt_pk_bf16_f32 v49, v34, v35
	v_mfma_f32_32x32x16_bf16 v[16:31], v[168:171], v[176:179], v[16:31]
	s_waitcnt vmcnt(2)
	v_mul_f32_e64 v32, v36, v242
	v_mul_f32_e64 v33, v37, v243
	v_mul_f32_e64 v34, v38, v244
	v_mul_f32_e64 v35, v39, v245
	v_cvt_pk_bf16_f32 v32, v32, v33
	v_cvt_pk_bf16_f32 v33, v34, v35
	ds_write2_b64 v112, v[48:49], v[32:33] offset0:8 offset1:10
	v_mfma_f32_32x32x16_bf16 v[16:31], v[196:199], v[188:191], v[16:31]
	s_waitcnt vmcnt(1)
	v_mul_f32_e64 v32, v40, v248
	v_mul_f32_e64 v33, v41, v249
	v_mul_f32_e64 v34, v42, v250
	v_mul_f32_e64 v35, v43, v251
	v_cvt_pk_bf16_f32 v36, v32, v33
	v_cvt_pk_bf16_f32 v37, v34, v35
	v_mfma_f32_32x32x16_bf16 v[16:31], v[148:151], v[204:207], v[16:31]
	s_waitcnt vmcnt(0)
	v_mul_f32_e64 v32, v44, v252
	v_mul_f32_e64 v33, v45, v253
	v_mul_f32_e64 v34, v46, v254
	v_mul_f32_e64 v35, v47, v255
	v_cvt_pk_bf16_f32 v32, v32, v33
	v_cvt_pk_bf16_f32 v33, v34, v35
	ds_write2_b64 v112, v[36:37], v[32:33] offset0:12 offset1:14
	global_load_dwordx4 v[222:225], v[210:211], off offset:256
	global_load_dwordx4 v[226:229], v[210:211], off offset:288
	global_load_dwordx4 v[230:233], v[210:211], off offset:320
	global_load_dwordx4 v[234:237], v[210:211], off offset:352
	global_load_dwordx4 v[238:241], v[210:211], off offset:384
	global_load_dwordx4 v[242:245], v[210:211], off offset:416
	global_load_dwordx4 v[248:251], v[210:211], off offset:448
	global_load_dwordx4 v[252:255], v[210:211], off offset:480
	v_mfma_f32_32x32x16_bf16 v[0:15], v[132:135], v[128:131], v[0:15]
	s_waitcnt vmcnt(7)
	s_nop 0
	v_mul_f32_e64 v16, v16, v222
	v_mul_f32_e64 v17, v17, v223
	v_mul_f32_e64 v18, v18, v224
	v_mul_f32_e64 v19, v19, v225
	v_cvt_pk_bf16_f32 v32, v16, v17
	v_cvt_pk_bf16_f32 v33, v18, v19
	v_mfma_f32_32x32x16_bf16 v[0:15], v[164:167], v[176:179], v[0:15]
	s_waitcnt vmcnt(6)
	v_mul_f32_e64 v16, v20, v226
	v_mul_f32_e64 v17, v21, v227
	v_mul_f32_e64 v18, v22, v228
	v_mul_f32_e64 v19, v23, v229
	v_cvt_pk_bf16_f32 v16, v16, v17
	v_cvt_pk_bf16_f32 v17, v18, v19
	ds_write2_b64 v112, v[32:33], v[16:17] offset0:16 offset1:18
	v_mfma_f32_32x32x16_bf16 v[0:15], v[200:203], v[188:191], v[0:15]
	s_waitcnt vmcnt(5)
	v_mul_f32_e64 v16, v24, v230
	v_mul_f32_e64 v17, v25, v231
	v_mul_f32_e64 v18, v26, v232
	v_mul_f32_e64 v19, v27, v233
	v_cvt_pk_bf16_f32 v20, v16, v17
	v_cvt_pk_bf16_f32 v21, v18, v19
	v_mfma_f32_32x32x16_bf16 v[0:15], v[152:155], v[204:207], v[0:15]
	s_waitcnt vmcnt(4)
	v_mul_f32_e64 v16, v28, v234
	v_mul_f32_e64 v17, v29, v235
	v_mul_f32_e64 v18, v30, v236
	v_mul_f32_e64 v19, v31, v237
	v_cvt_pk_bf16_f32 v16, v16, v17
	v_cvt_pk_bf16_f32 v17, v18, v19
	ds_write2_b64 v112, v[20:21], v[16:17] offset0:20 offset1:22
	s_waitcnt vmcnt(3)
	s_nop 1
	v_pk_mul_f32 v[0:1], v[0:1], v[238:239]
	v_pk_mul_f32 v[2:3], v[2:3], v[240:241]
	v_cvt_pk_bf16_f32 v16, v0, v1
	v_cvt_pk_bf16_f32 v17, v2, v3
	s_waitcnt vmcnt(2)
	v_pk_mul_f32 v[0:1], v[4:5], v[242:243]
	v_pk_mul_f32 v[2:3], v[6:7], v[244:245]
	v_cvt_pk_bf16_f32 v0, v0, v1
	v_cvt_pk_bf16_f32 v1, v2, v3
	ds_write2_b64 v112, v[16:17], v[0:1] offset0:24 offset1:26
	s_waitcnt vmcnt(1)
	v_pk_mul_f32 v[0:1], v[8:9], v[248:249]
	v_pk_mul_f32 v[2:3], v[10:11], v[250:251]
	v_cvt_pk_bf16_f32 v4, v0, v1
	v_cvt_pk_bf16_f32 v5, v2, v3
	s_waitcnt vmcnt(0)
	v_pk_mul_f32 v[0:1], v[12:13], v[252:253]
	v_pk_mul_f32 v[2:3], v[14:15], v[254:255]
	v_cvt_pk_bf16_f32 v0, v0, v1
	v_cvt_pk_bf16_f32 v1, v2, v3
	ds_write2_b64 v112, v[4:5], v[0:1] offset0:28 offset1:30
	s_waitcnt lgkmcnt(0)
	s_barrier
	s_branch .LBB0_225

; #define G_LOAD(pr, qr, kt_) if (MODE != 1) { _Pragma("unroll") for (int r = 0; r < NP; ++r) pr[r] = *(const u32x4*)(pp + (size_t)(r * 128) * ldp + (kt_) * BK); \
;                               _Pragma("unroll") for (int r = 0; r < NQ; ++r) qr[r] = *(const u32x4*)(qp + (size_t)(r * 128) * ldq + (kt_) * BK); }
; #define G_STORE(pr, qr, so_) { unsigned char* w_ = wP + (so_); \
;                               _Pragma("unroll") for (int r = 0; r < NP; ++r) *(u32x4*)(w_ + r * 128 * LROW) = pr[r]; \
;                               _Pragma("unroll") for (int r = 0; r < NQ; ++r) *(u32x4*)(w_ + BI * LROW + r * 128 * LROW) = qr[r]; }
; #define F_LOAD(fa, fb, so_, ks_) { _Pragma("unroll") for (int it = 0; it < WI; ++it) fa[it] = *(const bf16x8*)(rP + (so_) + it * 32 * LROW + (ks_) * 32); \
;                                   _Pragma("unroll") for (int jt = 0; jt < 2; ++jt) fb[jt] = *(const bf16x8*)(rQ + (so_) + jt * 32 * LROW + (ks_) * 32); }
; #define G_MFMA(fa, fb) if (MODE != 2) { _Pragma("unroll") for (int it = 0; it < WI; ++it) _Pragma("unroll") for (int jt = 0; jt < 2; ++jt) \
;                             acc[it][jt] = __builtin_amdgcn_mfma_f32_32x32x16_bf16(fa[it], fb[jt], acc[it][jt], 0, 0, 0); }
; #define SB __builtin_amdgcn_sched_barrier(0);
; #define G_LOAD(pr, qr, kt_) if (MODE != 1) { _Pragma("unroll") for (int r = 0; r < NP; ++r) pr[r] = *(const u32x4*)(pp + (size_t)(r * 128) * ldp + (kt_) * BK); \
;                               _Pragma("unroll") for (int r = 0; r < NQ; ++r) qr[r] = *(const u32x4*)(qp + (size_t)(r * 128) * ldq + (kt_) * BK); }
;     ...
;     for (int kt = 0; kt < nk; kt += 2) {
;         const int k3 = min(kt + 3, nk - 1), k4 = min(kt + 4, nk - 1);
;         SB
;         G_LOAD(pb, qb, k3)
;         F_LOAD(fa1, fb1, cur, 1)
;         SB
;         G_MFMA(fa0, fb0)
;         SB
;         G_STORE(pa, qa, wr)
;         F_LOAD(fa0, fb0, nxt, 0)
;         SB
;         G_MFMA(fa1, fb1)
;         SB
;         __syncthreads();
;         { const int t_ = cur; cur = nxt; nxt = wr; wr = t_; }
;         SB
;         G_LOAD(pa, qa, k4)
;         F_LOAD(fa1, fb1, cur, 1)
;         SB
;         G_MFMA(fa0, fb0)
;         SB
;         G_STORE(pb, qb, wr)
;         F_LOAD(fa0, fb0, nxt, 0)
;         SB
;         G_MFMA(fa1, fb1)
;         SB
;         __syncthreads();
;         { const int t_ = cur; cur = nxt; nxt = wr; wr = t_; }
;     }
.LBB0_553:
	s_mov_b32 s9, s8
	global_load_dwordx4 v[192:195], v[172:173], off offset:192
	global_load_dwordx4 v[196:199], v[176:177], off
	global_load_dwordx4 v[200:203], v[174:175], off offset:192
	global_load_dwordx4 v[204:207], v[178:179], off
	v_add_u32_e32 v220, s3, v171
	ds_read_b128 v[208:211], v220 offset:2080
	ds_read_b128 v[212:215], v220 offset:4640
	ds_read_b128 v[216:219], v220 offset:7200
	ds_read_b128 v[220:223], v220 offset:9760
	v_add_u32_e32 v228, s3, v191
	ds_read_b128 v[224:227], v228 offset:22560
	ds_read_b128 v[228:231], v228 offset:25120
	s_waitcnt lgkmcnt(9)
	v_mfma_f32_32x32x16_bf16 v[112:127], v[164:167], v[144:147], v[112:127]
	v_mfma_f32_32x32x16_bf16 v[48:63], v[164:167], v[148:151], v[48:63]
	s_waitcnt lgkmcnt(8)
	v_mfma_f32_32x32x16_bf16 v[96:111], v[160:163], v[144:147], v[96:111]
	v_mfma_f32_32x32x16_bf16 v[32:47], v[160:163], v[148:151], v[32:47]
	s_waitcnt lgkmcnt(7)
	v_mfma_f32_32x32x16_bf16 v[80:95], v[156:159], v[144:147], v[80:95]
	v_mfma_f32_32x32x16_bf16 v[16:31], v[156:159], v[148:151], v[16:31]
	s_waitcnt lgkmcnt(6)
	v_mfma_f32_32x32x16_bf16 v[64:79], v[152:155], v[144:147], v[64:79]
	v_mfma_f32_32x32x16_bf16 v[0:15], v[152:155], v[148:151], v[0:15]
	v_add_u32_e32 v144, s9, v168
	s_waitcnt vmcnt(7)
	ds_write_b128 v144, v[128:131] offset:2048
	s_waitcnt vmcnt(6)
	ds_write_b128 v144, v[132:135] offset:12288
	s_waitcnt vmcnt(5)
	ds_write_b128 v144, v[136:139] offset:22528
	s_waitcnt vmcnt(4)
	ds_write_b128 v144, v[140:143] offset:32768
	v_add_u32_e32 v232, s5, v171
	ds_read_b128 v[144:147], v232 offset:2048
	ds_read_b128 v[148:151], v232 offset:4608
	ds_read_b128 v[152:155], v232 offset:7168
	ds_read_b128 v[156:159], v232 offset:9728
	v_add_u32_e32 v233, s5, v191
	ds_read_b128 v[160:163], v233 offset:22528
	ds_read_b128 v[164:167], v233 offset:25088
	s_waitcnt lgkmcnt(11)
	v_mfma_f32_32x32x16_bf16 v[112:127], v[208:211], v[224:227], v[112:127]
	s_waitcnt lgkmcnt(10)
	v_mfma_f32_32x32x16_bf16 v[48:63], v[208:211], v[228:231], v[48:63]
	v_mfma_f32_32x32x16_bf16 v[96:111], v[212:215], v[224:227], v[96:111]
	v_mfma_f32_32x32x16_bf16 v[32:47], v[212:215], v[228:231], v[32:47]
	v_mfma_f32_32x32x16_bf16 v[80:95], v[216:219], v[224:227], v[80:95]
	v_mfma_f32_32x32x16_bf16 v[16:31], v[216:219], v[228:231], v[16:31]
	v_mfma_f32_32x32x16_bf16 v[64:79], v[220:223], v[224:227], v[64:79]
	v_mfma_f32_32x32x16_bf16 v[0:15], v[220:223], v[228:231], v[0:15]
	s_waitcnt lgkmcnt(0)
	s_barrier
	global_load_dwordx4 v[128:131], v[172:173], off offset:192
	global_load_dwordx4 v[132:135], v[176:177], off
	global_load_dwordx4 v[136:139], v[174:175], off offset:192
	global_load_dwordx4 v[140:143], v[178:179], off
	ds_read_b128 v[208:211], v232 offset:2080
	ds_read_b128 v[212:215], v232 offset:4640
	ds_read_b128 v[216:219], v232 offset:7200
	ds_read_b128 v[220:223], v232 offset:9760
	ds_read_b128 v[224:227], v233 offset:22560
	ds_read_b128 v[228:231], v233 offset:25120
	v_mfma_f32_32x32x16_bf16 v[112:127], v[144:147], v[160:163], v[112:127]
	v_mfma_f32_32x32x16_bf16 v[48:63], v[144:147], v[164:167], v[48:63]
	v_mfma_f32_32x32x16_bf16 v[96:111], v[148:151], v[160:163], v[96:111]
	v_mfma_f32_32x32x16_bf16 v[32:47], v[148:151], v[164:167], v[32:47]
	v_mfma_f32_32x32x16_bf16 v[80:95], v[152:155], v[160:163], v[80:95]
	v_mfma_f32_32x32x16_bf16 v[16:31], v[152:155], v[164:167], v[16:31]
	v_mfma_f32_32x32x16_bf16 v[64:79], v[156:159], v[160:163], v[64:79]
	v_mfma_f32_32x32x16_bf16 v[0:15], v[156:159], v[164:167], v[0:15]
	v_add_u32_e32 v144, s3, v168
	s_waitcnt vmcnt(7)
	ds_write_b128 v144, v[192:195] offset:2048
	s_waitcnt vmcnt(6)
	ds_write_b128 v144, v[196:199] offset:12288
	s_waitcnt vmcnt(5)
	ds_write_b128 v144, v[200:203] offset:22528
	s_waitcnt vmcnt(4)
	ds_write_b128 v144, v[204:207] offset:32768
	v_add_u32_e32 v144, s9, v171
	ds_read_b128 v[164:167], v144 offset:2048
	ds_read_b128 v[160:163], v144 offset:4608
	ds_read_b128 v[156:159], v144 offset:7168
	ds_read_b128 v[152:155], v144 offset:9728
	v_add_u32_e32 v148, s9, v191
	ds_read_b128 v[144:147], v148 offset:22528
	ds_read_b128 v[148:151], v148 offset:25088
	s_waitcnt lgkmcnt(11)
	v_mfma_f32_32x32x16_bf16 v[112:127], v[208:211], v[224:227], v[112:127]
	s_waitcnt lgkmcnt(10)
	v_mfma_f32_32x32x16_bf16 v[48:63], v[208:211], v[228:231], v[48:63]
	v_mfma_f32_32x32x16_bf16 v[96:111], v[212:215], v[224:227], v[96:111]
	v_mfma_f32_32x32x16_bf16 v[32:47], v[212:215], v[228:231], v[32:47]
	v_mfma_f32_32x32x16_bf16 v[80:95], v[216:219], v[224:227], v[80:95]
	v_mfma_f32_32x32x16_bf16 v[16:31], v[216:219], v[228:231], v[16:31]
	v_mfma_f32_32x32x16_bf16 v[64:79], v[220:223], v[224:227], v[64:79]
	v_mfma_f32_32x32x16_bf16 v[0:15], v[220:223], v[228:231], v[0:15]
	s_and_b64 vcc, exec, s[6:7]
	s_mov_b64 s[6:7], 0
	s_mov_b32 s8, s5
	s_mov_b32 s5, s3
	s_mov_b32 s3, s9
	s_waitcnt lgkmcnt(0)
	s_barrier
	s_cbranch_vccnz .LBB0_553
; DI u32x2 pk4(float a, float b, float c, float d) { u32x2 r; r.x = pk2(a, b); r.y = pk2(c, d); return r; }
; template <int WI, int WGJ, class GetF, class FinF>
; DI void staged_rows(unsigned char* lds, int tid, GetF get, FinF fin) {
;     ...
;     for (int jt = 0; jt < 2; ++jt) {
;         unsigned char* wrow = lds + (wj * 32 + ln) * RS + (wi * WI * 32 + 4 * h) * 2;
; #pragma unroll
;         for (int it = 0; it < WI; ++it)
; #pragma unroll
;             for (int g = 0; g < 4; ++g) *(u32x2*)(wrow + (it * 32 + 8 * g) * 2) = get(it, jt, g);
;         __syncthreads();
; DI void phase2(const Params& p, unsigned char* smem, int tid) {
;     ...
;             staged_rows<4, 4>(lds, te,
;                 [&](int it, int jt, int g) { const f32x4 rs = *(const f32x4*)((const float*)(ws + OFF_RKV) + tt * 256 + wi * 128 + it * 32 + 8 * g + 4 * h);
;                     return pk4(acc[it][jt][4 * g] * rs[0], acc[it][jt][4 * g + 1] * rs[1], acc[it][jt][4 * g + 2] * rs[2], acc[it][jt][4 * g + 3] * rs[3]); },
	s_waitcnt vmcnt(2)
	v_mov_b32_e32 v134, v188
	s_lshl_b32 s4, s4, 8
	v_ashrrev_i32_e32 v128, 6, v134
	v_lshrrev_b32_e32 v129, 30, v128
	v_add_u32_e32 v129, v128, v129
	v_and_b32_e32 v130, 0x7ffffc, v129
	v_sub_u32_e32 v128, v128, v130
	v_and_b32_e32 v130, 31, v134
	v_lshl_or_b32 v128, v128, 5, v130
	v_lshlrev_b32_e32 v129, 6, v129
	v_mul_lo_u32 v128, v128, s80
	v_and_b32_e32 v129, 0xffffff00, v129
	v_lshrrev_b32_e32 v130, 2, v134
	v_and_b32_e32 v130, 8, v130
	v_add3_u32 v128, 0, v128, v129
	v_add_u32_e32 v135, v128, v130
	s_ashr_i32 s5, s4, 31
	v_ashrrev_i32_e32 v128, 1, v134
	s_lshl_b32 s2, s2, 8
	s_lshl_b64 s[6:7], s[4:5], 2
	v_and_b32_e32 v128, 0xffffff80, v128
	s_add_u32 s8, s30, s6
	v_ashrrev_i32_e32 v129, 31, v128
	s_addc_u32 s9, s31, s7
	s_waitcnt vmcnt(1)
	v_lshlrev_b64 v[136:137], 2, v[128:129]
	v_lshrrev_b32_e32 v130, 1, v134
	v_lshl_add_u64 v[128:129], s[8:9], 0, v[136:137]
	v_and_b32_e32 v168, 16, v130
	v_lshl_add_u64 v[128:129], v[128:129], 0, v[168:169]
	global_load_dwordx4 v[232:235], v[128:129], off
	global_load_dwordx4 v[236:239], v[128:129], off offset:32
	global_load_dwordx4 v[240:243], v[128:129], off offset:64
	global_load_dwordx4 v[248:251], v[128:129], off offset:96
	global_load_dwordx4 v[252:255], v[128:129], off offset:128
	s_add_u32 s6, s22, s6
	s_addc_u32 s7, s23, s7
	s_mov_b32 s3, 0x2bf000
	v_add_u32_e32 v135, 0x800, v135
	s_waitcnt vmcnt(4)
	v_pk_mul_f32 v[112:113], v[112:113], v[232:233]
	v_pk_mul_f32 v[114:115], v[114:115], v[234:235]
	v_cvt_pk_bf16_f32 v112, v112, v113
	v_cvt_pk_bf16_f32 v113, v114, v115
	v_lshl_add_u64 v[114:115], s[6:7], 0, v[136:137]
	v_lshl_add_u64 v[132:133], v[114:115], 0, v[168:169]
	v_add_co_u32_e32 v130, vcc, s3, v132
	s_mov_b64 s[6:7], 0x2bf820
	s_nop 0
	v_addc_co_u32_e32 v131, vcc, 0, v133, vcc
	v_lshl_add_u64 v[114:115], v[132:133], 0, s[6:7]
	s_mov_b64 s[6:7], 0x2bf840
	s_mov_b32 s3, 0
	s_waitcnt vmcnt(3)
	v_pk_mul_f32 v[116:117], v[116:117], v[236:237]
	v_pk_mul_f32 v[118:119], v[118:119], v[238:239]
	v_cvt_pk_bf16_f32 v116, v116, v117
	v_cvt_pk_bf16_f32 v117, v118, v119
	ds_write2_b64 v135, v[112:113], v[116:117] offset1:2
	v_lshl_add_u64 v[112:113], v[132:133], 0, s[6:7]
	s_mov_b64 s[6:7], 0x2bf860
	s_waitcnt vmcnt(2)
	v_pk_mul_f32 v[118:119], v[122:123], v[242:243]
	v_pk_mul_f32 v[116:117], v[120:121], v[240:241]
	v_cvt_pk_bf16_f32 v123, v118, v119
	v_cvt_pk_bf16_f32 v122, v116, v117
	v_lshl_add_u64 v[116:117], v[132:133], 0, s[6:7]
	s_mov_b64 s[6:7], 0x2bf880
	s_waitcnt vmcnt(1)
	v_pk_mul_f32 v[118:119], v[124:125], v[248:249]
	v_pk_mul_f32 v[120:121], v[126:127], v[250:251]
	v_cvt_pk_bf16_f32 v118, v118, v119
	v_cvt_pk_bf16_f32 v119, v120, v121
	ds_write2_b64 v135, v[122:123], v[118:119] offset0:4 offset1:6
	v_lshl_add_u64 v[118:119], v[132:133], 0, s[6:7]
	s_mov_b64 s[6:7], 0x2bf8a0
	s_waitcnt vmcnt(0)
	v_pk_mul_f32 v[96:97], v[96:97], v[252:253]
	v_pk_mul_f32 v[98:99], v[98:99], v[254:255]
	global_load_dwordx4 v[232:235], v[128:129], off offset:160
	global_load_dwordx4 v[236:239], v[128:129], off offset:192
	global_load_dwordx4 v[240:243], v[128:129], off offset:224
	global_load_dwordx4 v[248:251], v[128:129], off offset:256
	global_load_dwordx4 v[252:255], v[128:129], off offset:288
	v_cvt_pk_bf16_f32 v125, v98, v99
	v_cvt_pk_bf16_f32 v124, v96, v97
	v_lshl_add_u64 v[96:97], v[132:133], 0, s[6:7]
	s_mov_b64 s[6:7], 0x2bf8c0
	s_waitcnt vmcnt(4)
	v_pk_mul_f32 v[98:99], v[100:101], v[232:233]
	v_pk_mul_f32 v[100:101], v[102:103], v[234:235]
	v_cvt_pk_bf16_f32 v98, v98, v99
	v_cvt_pk_bf16_f32 v99, v100, v101
	ds_write2_b64 v135, v[124:125], v[98:99] offset0:8 offset1:10
	v_lshl_add_u64 v[98:99], v[132:133], 0, s[6:7]
	s_mov_b64 s[6:7], 0x2bf8e0
	s_waitcnt vmcnt(3)
	v_pk_mul_f32 v[102:103], v[106:107], v[238:239]
	v_pk_mul_f32 v[100:101], v[104:105], v[236:237]
	v_cvt_pk_bf16_f32 v107, v102, v103
	v_cvt_pk_bf16_f32 v106, v100, v101
	v_lshl_add_u64 v[100:101], v[132:133], 0, s[6:7]
	s_mov_b64 s[6:7], 0x2bf900
	s_waitcnt vmcnt(2)
	v_pk_mul_f32 v[102:103], v[108:109], v[240:241]
	v_pk_mul_f32 v[104:105], v[110:111], v[242:243]
	v_cvt_pk_bf16_f32 v102, v102, v103
	v_cvt_pk_bf16_f32 v103, v104, v105
	ds_write2_b64 v135, v[106:107], v[102:103] offset0:12 offset1:14
	v_lshl_add_u64 v[102:103], v[132:133], 0, s[6:7]
	s_mov_b64 s[6:7], 0x2bf920
	v_lshl_add_u64 v[108:109], v[132:133], 0, s[60:61]
	s_waitcnt vmcnt(1)
	v_pk_mul_f32 v[80:81], v[80:81], v[248:249]
	v_pk_mul_f32 v[82:83], v[82:83], v[250:251]
	v_cvt_pk_bf16_f32 v106, v80, v81
	v_cvt_pk_bf16_f32 v107, v82, v83
	v_lshl_add_u64 v[104:105], v[132:133], 0, s[6:7]
	s_waitcnt vmcnt(0)
	v_pk_mul_f32 v[80:81], v[84:85], v[252:253]
	v_pk_mul_f32 v[82:83], v[86:87], v[254:255]
	v_cvt_pk_bf16_f32 v80, v80, v81
	v_cvt_pk_bf16_f32 v81, v82, v83
	ds_write2_b64 v135, v[106:107], v[80:81] offset0:16 offset1:18
	global_load_dwordx4 v[232:235], v[128:129], off offset:320
	global_load_dwordx4 v[236:239], v[128:129], off offset:352
	global_load_dwordx4 v[240:243], v[128:129], off offset:384
	global_load_dwordx4 v[248:251], v[128:129], off offset:416
	global_load_dwordx4 v[252:255], v[128:129], off offset:448
	v_lshl_add_u64 v[106:107], v[132:133], 0, s[44:45]
	s_waitcnt vmcnt(4)
	v_pk_mul_f32 v[80:81], v[88:89], v[232:233]
	v_pk_mul_f32 v[82:83], v[90:91], v[234:235]
	v_cvt_pk_bf16_f32 v84, v80, v81
	v_cvt_pk_bf16_f32 v85, v82, v83
	v_lshl_add_u64 v[88:89], v[132:133], 0, s[46:47]
	v_lshl_add_u64 v[90:91], v[132:133], 0, s[48:49]
	s_waitcnt vmcnt(3)
	v_pk_mul_f32 v[80:81], v[92:93], v[236:237]
	v_pk_mul_f32 v[82:83], v[94:95], v[238:239]
	v_cvt_pk_bf16_f32 v80, v80, v81
	v_cvt_pk_bf16_f32 v81, v82, v83
	ds_write2_b64 v135, v[84:85], v[80:81] offset0:20 offset1:22
	v_lshl_add_u64 v[92:93], v[132:133], 0, s[52:53]
	v_lshl_add_u64 v[94:95], v[132:133], 0, s[54:55]
	s_waitcnt vmcnt(2)
	v_pk_mul_f32 v[64:65], v[64:65], v[240:241]
	v_pk_mul_f32 v[66:67], v[66:67], v[242:243]
	v_cvt_pk_bf16_f32 v80, v64, v65
	v_cvt_pk_bf16_f32 v81, v66, v67
	s_waitcnt vmcnt(1)
	v_pk_mul_f32 v[64:65], v[68:69], v[248:249]
	v_pk_mul_f32 v[66:67], v[70:71], v[250:251]
	v_cvt_pk_bf16_f32 v64, v64, v65
	v_cvt_pk_bf16_f32 v65, v66, v67
	ds_write2_b64 v135, v[80:81], v[64:65] offset0:24 offset1:26
	s_waitcnt vmcnt(0)
	v_pk_mul_f32 v[64:65], v[72:73], v[252:253]
	v_pk_mul_f32 v[66:67], v[74:75], v[254:255]
	v_cvt_pk_bf16_f32 v68, v64, v65
	v_cvt_pk_bf16_f32 v69, v66, v67
	global_load_dwordx4 v[232:235], v[128:129], off offset:480
	s_waitcnt vmcnt(0)
	v_pk_mul_f32 v[64:65], v[76:77], v[232:233]
	v_pk_mul_f32 v[66:67], v[78:79], v[234:235]
	v_cvt_pk_bf16_f32 v64, v64, v65
	v_cvt_pk_bf16_f32 v65, v66, v67
	ds_write2_b64 v135, v[68:69], v[64:65] offset0:28 offset1:30
	s_waitcnt lgkmcnt(0)
	s_barrier
	s_branch .LBB0_556

;     ...
;     f32x16 o[2];
; #pragma unroll
;     for (int d = 0; d < 2; ++d)
; #pragma unroll
;         for (int r = 0; r < 16; ++r) o[d][r] = 0.f;
;     float m = -INFINITY, lsum = 0.f;
;     ...
;     const int jlast = nkt - 1;
;     gload(jlast); lstore(0);
;     __syncthreads();
;     m = -1e30f;
.LBB0_745:
	s_or_b64 exec, exec, s[10:11]
	s_and_b32 s10, s13, 0x1fc0
	v_add_u32_e32 v1, s12, v151
	v_subrev_u32_e32 v219, s10, v1
	v_add_u32_e32 v1, s10, v184
	s_xor_b64 s[48:49], s[8:9], -1
	v_mad_i64_i32 v[176:177], s[8:9], v1, s70, v[172:173]
	v_add_u32_e32 v1, s10, v189
	v_mov_b32_e32 v14, v0
	v_mov_b32_e32 v15, v0
	v_mad_i64_i32 v[178:179], s[8:9], v1, s70, v[174:175]
	v_mov_b32_e32 v1, v0
	v_mov_b32_e32 v2, v0
	v_mov_b32_e32 v3, v0
	v_mov_b32_e32 v4, v0
	v_mov_b32_e32 v5, v0
	v_mov_b32_e32 v6, v0
	v_mov_b32_e32 v7, v0
	v_mov_b32_e32 v8, v0
	v_mov_b32_e32 v9, v0
	v_mov_b32_e32 v10, v0
	v_mov_b32_e32 v11, v0
	v_mov_b32_e32 v12, v0
	v_mov_b32_e32 v13, v0
	v_mov_b64_e32 v[32:33], v[14:15]
	v_mov_b64_e32 v[30:31], v[12:13]
	v_mov_b64_e32 v[28:29], v[10:11]
	v_mov_b64_e32 v[26:27], v[8:9]
	v_mov_b64_e32 v[24:25], v[6:7]
	v_mov_b64_e32 v[22:23], v[4:5]
	v_mov_b64_e32 v[20:21], v[2:3]
	v_mov_b64_e32 v[18:19], v[0:1]
	v_mov_b64_e32 v[16:17], v[14:15]
	s_lshr_b32 s2, s13, 6
	v_add_u32_e32 v218, 31, v159
	s_sub_i32 s42, s10, 64
	s_mov_b32 s60, 0
	v_mov_b32_e32 v220, 0
	v_mov_b32_e32 v221, 0xf149f2ca
	v_mov_b32_e32 v230, 0
	v_mov_b32_e32 v231, 0
	v_mov_b32_e32 v232, 0
	v_mov_b32_e32 v233, 0
	v_mov_b32_e32 v234, 0
	v_mov_b32_e32 v235, 0
	v_mov_b32_e32 v236, 0
	v_mov_b32_e32 v237, 0
	v_mov_b32_e32 v238, 0
	v_mov_b32_e32 v239, 0
	v_mov_b32_e32 v240, 0
	v_mov_b32_e32 v241, 0
	v_mov_b32_e32 v242, 0
	v_mov_b32_e32 v243, 0
	v_mov_b32_e32 v244, 0
	v_mov_b32_e32 v245, 0
	v_mov_b32_e32 v246, 0
	v_mov_b64_e32 v[14:15], v[12:13]
	v_mov_b64_e32 v[12:13], v[10:11]
	v_mov_b64_e32 v[10:11], v[8:9]
	v_mov_b64_e32 v[8:9], v[6:7]
	v_mov_b64_e32 v[6:7], v[4:5]
	v_mov_b64_e32 v[4:5], v[2:3]
	v_mov_b64_e32 v[2:3], v[0:1]
	s_waitcnt vmcnt(0)
	ds_write2_b64 v213, v[98:99], v[100:101] offset1:1
	s_waitcnt lgkmcnt(0)
	s_barrier
	s_branch .LBB0_748

;     ...
;         if (!wdone && 64 * j <= qw0 + 31) {
;             const unsigned char* kb = lds + st * STG;
;             const unsigned char* vb = kb + KBYTES;
;             f32x16 s[2];
;             if (FOX) {
;                 const float* bl = (const float*)(vb + VBYTES);
; #pragma unroll
;                 for (int t2 = 0; t2 < 2; ++t2)
; #pragma unroll
;                     for (int g = 0; g < 4; ++g) {
;                         const f32x4 b4 = *(const f32x4*)(bl + t2 * 32 + 8 * g + 4 * h);
;                         s[t2][4 * g] = b4[0]; s[t2][4 * g + 1] = b4[1]; s[t2][4 * g + 2] = b4[2]; s[t2][4 * g + 3] = b4[3];
;                     }
;             } else {
; #pragma unroll
;                 for (int t2 = 0; t2 < 2; ++t2)
; #pragma unroll
;                     for (int r = 0; r < 16; ++r) s[t2][r] = 0.f;
;             }
;             bf16x8 kf[KS][2];
; #pragma unroll
;             for (int ks = 0; ks < KS; ++ks)
; #pragma unroll
;                 for (int t2 = 0; t2 < 2; ++t2) kf[ks][t2] = *(const bf16x8*)(kb + (t2 * 32 + ln) * KROW + ks * 32 + h * 16);
;             __builtin_amdgcn_sched_barrier(0);
; #pragma unroll
;             for (int ks = 0; ks < KS; ++ks)
; #pragma unroll
;                 for (int t2 = 0; t2 < 2; ++t2) s[t2] = __builtin_amdgcn_mfma_f32_32x32x16_bf16(kf[ks][t2], qf[ks], s[t2], 0, 0, 0);
;             __builtin_amdgcn_sched_barrier(0);
;             u32x2 vf[4][2][2];
; #pragma unroll
;             for (int kk = 0; kk < 4; ++kk)
; #pragma unroll
;                 for (int d = 0; d < 2; ++d) {
;                     const unsigned char* va = vb + (d * 32 + ln) * VROW + (16 * kk + 4 * h) * 2;
;                     vf[kk][d][0] = *(const u32x2*)va; vf[kk][d][1] = *(const u32x2*)(va + 16);
;                 }
;             __builtin_amdgcn_sched_barrier(0);
;             if (64 * j + 63 > qw0) {
;                 const int thr = myq - 64 * j - 4 * h;
; #pragma unroll
;                 for (int t2 = 0; t2 < 2; ++t2)
; #pragma unroll
;                     for (int r = 0; r < 16; ++r) { if (((r & 3) + 8 * (r >> 2) + 32 * t2) > thr) s[t2][r] = -INFINITY; }
;             }
.LBB0_754:
	s_add_i32 s8, s42, 64
	s_and_b32 s61, s60, 1
	v_cmp_le_i32_e32 vcc, s8, v218
	s_and_saveexec_b64 s[66:67], vcc
	s_cbranch_execz .LBB0_760
	s_mul_i32 s8, s61, 0x5700
	s_add_i32 s8, s8, 0
	v_add3_u32 v1, s8, v150, v200
	ds_read_b128 v[34:37], v1 offset:2048
	ds_read_b128 v[102:105], v1 offset:2080
	ds_read_b128 v[38:41], v1 offset:8704
	ds_read_b128 v[106:109], v1 offset:8736
	ds_read_b128 v[110:113], v1 offset:2112
	ds_read_b128 v[114:117], v1 offset:2144
	ds_read_b128 v[118:121], v1 offset:8768
	ds_read_b128 v[122:125], v1 offset:8800
	ds_read_b128 v[126:129], v1 offset:2176
	ds_read_b128 v[130:133], v1 offset:2208
	ds_read_b128 v[222:225], v1 offset:8832
	ds_read_b128 v[226:229], v1 offset:8864
	s_waitcnt lgkmcnt(11)
	v_mfma_f32_32x32x16_bf16 v[50:65], v[34:37], v[66:69], v[230:245]
	s_waitcnt lgkmcnt(9)
	v_mfma_f32_32x32x16_bf16 v[34:49], v[38:41], v[66:69], v[230:245]
	v_mfma_f32_32x32x16_bf16 v[50:65], v[102:105], v[70:73], v[50:65]
	s_waitcnt lgkmcnt(8)
	v_mfma_f32_32x32x16_bf16 v[34:49], v[106:109], v[70:73], v[34:49]
	s_waitcnt lgkmcnt(7)
	v_mfma_f32_32x32x16_bf16 v[50:65], v[110:113], v[74:77], v[50:65]
	s_waitcnt lgkmcnt(5)
	v_mfma_f32_32x32x16_bf16 v[34:49], v[118:121], v[74:77], v[34:49]
	v_mfma_f32_32x32x16_bf16 v[50:65], v[114:117], v[78:81], v[50:65]
	s_waitcnt lgkmcnt(4)
	v_mfma_f32_32x32x16_bf16 v[34:49], v[122:125], v[78:81], v[34:49]
	s_waitcnt lgkmcnt(3)
	v_mfma_f32_32x32x16_bf16 v[50:65], v[126:129], v[82:85], v[50:65]
	s_waitcnt lgkmcnt(1)
	v_mfma_f32_32x32x16_bf16 v[34:49], v[222:225], v[82:85], v[34:49]
	v_mfma_f32_32x32x16_bf16 v[50:65], v[130:133], v[86:89], v[50:65]
	s_waitcnt lgkmcnt(0)
	v_mfma_f32_32x32x16_bf16 v[34:49], v[226:229], v[86:89], v[34:49]
	v_add3_u32 v1, s8, v152, v181
	v_add_u32_e32 v102, 0x3800, v1
	v_add_u32_e32 v1, 0x4800, v1
	ds_read2_b64 v[130:133], v102 offset0:128 offset1:130
	ds_read2_b64 v[122:125], v102 offset0:132 offset1:134
	ds_read2_b64 v[126:129], v1 offset0:160 offset1:162
	ds_read2_b64 v[118:121], v1 offset0:164 offset1:166
	ds_read2_b64 v[114:117], v102 offset0:136 offset1:138
	ds_read2_b64 v[110:113], v1 offset0:168 offset1:170
	ds_read2_b64 v[106:109], v102 offset0:140 offset1:142
	ds_read2_b64 v[102:105], v1 offset0:172 offset1:174
	s_add_i32 s8, s42, 0x7f
	v_cmp_gt_i32_e32 vcc, s8, v159
	s_and_saveexec_b64 s[68:69], vcc
	s_cbranch_execz .LBB0_757
	v_cmp_gt_i32_e32 vcc, 0, v219
	v_cmp_gt_i32_e64 s[8:9], 1, v219
	s_and_b64 vcc, s[8:9], vcc
	v_cndmask_b32_e32 v50, v50, v217, vcc
	v_cmp_lt_i32_e32 vcc, 1, v219
	v_cmp_gt_i32_e64 s[38:39], 58, v219
	v_cmp_gt_i32_e64 s[40:41], 59, v219
	v_cndmask_b32_e32 v52, v217, v52, vcc
	v_cmp_lt_i32_e32 vcc, 2, v219
	v_cmp_gt_i32_e64 s[36:37], 57, v219
	s_and_b64 s[38:39], s[40:41], s[38:39]
	v_cndmask_b32_e32 v53, v217, v53, vcc
	v_cmp_lt_i32_e32 vcc, 7, v219
	v_cmp_gt_i32_e64 s[34:35], 56, v219
	s_and_b64 s[36:37], s[38:39], s[36:37]
	v_cndmask_b32_e32 v54, v217, v54, vcc
	v_cmp_lt_i32_e32 vcc, 8, v219
	v_cmp_gt_i32_e64 s[30:31], 51, v219
	s_and_b64 s[34:35], s[36:37], s[34:35]
	v_cndmask_b32_e32 v55, v217, v55, vcc
	v_cmp_lt_i32_e32 vcc, 9, v219
	v_cmp_gt_i32_e64 s[28:29], 50, v219
	s_and_b64 s[30:31], s[34:35], s[30:31]
	v_cndmask_b32_e32 v56, v217, v56, vcc
	v_cmp_lt_i32_e32 vcc, 10, v219
	v_cmp_gt_i32_e64 s[26:27], 49, v219
	s_and_b64 s[28:29], s[30:31], s[28:29]
	v_cndmask_b32_e32 v57, v217, v57, vcc
	v_cmp_lt_i32_e32 vcc, 15, v219
	v_cmp_gt_i32_e64 s[24:25], 48, v219
	s_and_b64 s[26:27], s[28:29], s[26:27]
	v_cndmask_b32_e32 v58, v217, v58, vcc
	v_cmp_lt_i32_e32 vcc, 16, v219
	v_cmp_gt_i32_e64 s[22:23], 43, v219
	s_and_b64 s[24:25], s[26:27], s[24:25]
	v_cndmask_b32_e32 v59, v217, v59, vcc
	v_cmp_lt_i32_e32 vcc, 17, v219
	v_cmp_gt_i32_e64 s[20:21], 42, v219
	s_and_b64 s[22:23], s[24:25], s[22:23]
	v_cndmask_b32_e32 v60, v217, v60, vcc
	v_cmp_lt_i32_e32 vcc, 18, v219
	v_cmp_gt_i32_e64 s[18:19], 41, v219
	s_and_b64 s[20:21], s[22:23], s[20:21]
	v_cndmask_b32_e32 v61, v217, v61, vcc
	v_cmp_lt_i32_e32 vcc, 23, v219
	v_cmp_gt_i32_e64 s[14:15], 40, v219
	s_and_b64 s[18:19], s[20:21], s[18:19]
	v_cndmask_b32_e32 v62, v217, v62, vcc
	v_cmp_lt_i32_e32 vcc, 24, v219
	v_cmp_gt_i32_e64 s[12:13], 35, v219
	s_and_b64 s[14:15], s[18:19], s[14:15]
	v_cndmask_b32_e32 v63, v217, v63, vcc
	v_cmp_lt_i32_e32 vcc, 25, v219
	v_cmp_gt_i32_e64 s[10:11], 34, v219
	s_and_b64 s[12:13], s[14:15], s[12:13]
	v_cndmask_b32_e64 v51, v51, v217, s[8:9]
	v_cndmask_b32_e32 v64, v217, v64, vcc
	v_cmp_lt_i32_e32 vcc, 26, v219
	v_cmp_gt_i32_e64 s[8:9], 33, v219
	s_and_b64 s[10:11], s[12:13], s[10:11]
	v_cndmask_b32_e32 v1, v217, v65, vcc
	v_cmp_gt_i32_e32 vcc, 32, v219
	s_and_b64 s[8:9], s[10:11], s[8:9]
	s_and_b64 vcc, s[8:9], vcc
	v_cndmask_b32_e64 v49, v49, v217, s[40:41]
	v_cndmask_b32_e64 v48, v48, v217, s[38:39]
	v_cndmask_b32_e64 v47, v47, v217, s[36:37]
	v_cndmask_b32_e64 v46, v46, v217, s[34:35]
	v_cndmask_b32_e64 v45, v45, v217, s[30:31]
	v_cndmask_b32_e64 v44, v44, v217, s[28:29]
	v_cndmask_b32_e64 v43, v43, v217, s[26:27]
	v_cndmask_b32_e64 v42, v42, v217, s[24:25]
	v_cndmask_b32_e64 v41, v41, v217, s[22:23]
	v_cndmask_b32_e64 v40, v40, v217, s[20:21]
	v_cndmask_b32_e64 v39, v39, v217, s[18:19]
	v_cndmask_b32_e64 v38, v38, v217, s[14:15]
	v_cndmask_b32_e64 v37, v37, v217, s[12:13]
	v_cndmask_b32_e64 v36, v36, v217, s[10:11]
	v_cndmask_b32_e64 v35, v35, v217, s[8:9]
	v_cndmask_b32_e32 v65, v65, v1, vcc
	v_cndmask_b32_e32 v34, v34, v217, vcc
;     ...
;             float mxa[2];
; #pragma unroll
;             for (int t2 = 0; t2 < 2; ++t2) {
;                 float x0 = fmaxf(fmaxf(s[t2][0], s[t2][1]), s[t2][2]);
;                 float x1 = fmaxf(fmaxf(s[t2][3], s[t2][4]), s[t2][5]);
;                 float x2 = fmaxf(fmaxf(s[t2][6], s[t2][7]), s[t2][8]);
;                 float x3 = fmaxf(fmaxf(s[t2][9], s[t2][10]), s[t2][11]);
;                 float x4 = fmaxf(fmaxf(s[t2][12], s[t2][13]), s[t2][14]);
;                 mxa[t2] = fmaxf(fmaxf(fmaxf(x0, x1), x2), fmaxf(fmaxf(x3, x4), s[t2][15]));
;             }
;             float mx = fmaxf(mxa[0], mxa[1]);
;             { const auto sw = __builtin_amdgcn_permlane32_swap(__float_as_uint(mx), __float_as_uint(mx), false, false);
;               mx = fmaxf(__uint_as_float(sw[0]), __uint_as_float(sw[1])); }
;             if (__builtin_amdgcn_ballot_w64(mx > m + 8.0f) != 0ull) {
;                 const float mn = fmaxf(m, mx);
;                 const float alpha = __builtin_amdgcn_exp2f(m - mn);
;                 m = mn;
;                 lsum *= alpha;
; #pragma unroll
;                 for (int d = 0; d < 2; ++d)
; #pragma unroll
;                     for (int r = 0; r < 16; ++r) o[d][r] *= alpha;
;             }
;             float ps0 = 0.f, ps1 = 0.f, ps2 = 0.f, ps3 = 0.f;
; #pragma unroll
;             for (int t2 = 0; t2 < 2; ++t2)
; #pragma unroll
;                 for (int r = 0; r < 16; r += 4) {
;                     const float e0 = __builtin_amdgcn_exp2f(s[t2][r] - m), e1 = __builtin_amdgcn_exp2f(s[t2][r + 1] - m);
;                     const float e2 = __builtin_amdgcn_exp2f(s[t2][r + 2] - m), e3 = __builtin_amdgcn_exp2f(s[t2][r + 3] - m);
;                     s[t2][r] = e0; s[t2][r + 1] = e1; s[t2][r + 2] = e2; s[t2][r + 3] = e3;
;                     ps0 += e0; ps1 += e1; ps2 += e2; ps3 += e3;
;                 }
;             lsum += (ps0 + ps1) + (ps2 + ps3);
.LBB0_757:
	s_or_b64 exec, exec, s[68:69]
	v_max3_f32 v1, v50, v51, v52
	v_max3_f32 v222, v53, v54, v55
	v_max3_f32 v223, v56, v57, v58
	v_max3_f32 v224, v59, v60, v61
	v_max3_f32 v225, v62, v63, v64
	v_max3_f32 v1, v1, v222, v223
	v_max3_f32 v222, v224, v225, v65
	v_max_f32_e32 v223, v35, v35
	v_max_f32_e32 v224, v34, v34
	v_max_f32_e32 v223, v224, v223
	v_max3_f32 v224, v37, v38, v39
	v_max3_f32 v226, v43, v44, v45
	v_max3_f32 v227, v46, v47, v48
	v_max3_f32 v225, v40, v41, v42
	v_max3_f32 v223, v223, v36, v224
	v_max3_f32 v224, v226, v227, v49
	v_max3_f32 v223, v223, v225, v224
	v_max3_f32 v1, v1, v222, v223
	v_mov_b32_e32 v222, v1
	s_nop 1
	v_permlane32_swap_b32_e32 v1, v222
	v_max_f32_e32 v222, v222, v222
	v_max_f32_e32 v1, v1, v1
	v_max_f32_e32 v1, v1, v222
	v_add_f32_e32 v1, v1, v246
	v_add_f32_e32 v222, 0x41000000, v221
	v_cmp_gt_f32_e32 vcc, v1, v222
	s_cbranch_vccz .LBB0_759
	v_max_f32_e32 v1, v1, v1
	v_max_f32_e32 v222, v221, v221
	v_max_f32_e32 v1, v222, v1
	v_sub_f32_e32 v221, v221, v1
	v_exp_f32_e32 v222, v221
	v_mov_b32_e32 v221, v1
	v_cmp_lt_f32_e32 vcc, 0xefa18f08, v1
	s_nop 1
	v_cndmask_b32_e32 v224, 0, v1, vcc
	v_sub_f32_e32 v223, v224, v246
	v_sub_f32_e32 v50, v50, v223
	v_sub_f32_e32 v51, v51, v223
	v_sub_f32_e32 v52, v52, v223
	v_sub_f32_e32 v53, v53, v223
	v_sub_f32_e32 v54, v54, v223
	v_sub_f32_e32 v55, v55, v223
	v_sub_f32_e32 v56, v56, v223
	v_sub_f32_e32 v57, v57, v223
	v_sub_f32_e32 v58, v58, v223
	v_sub_f32_e32 v59, v59, v223
	v_sub_f32_e32 v60, v60, v223
	v_sub_f32_e32 v61, v61, v223
	v_sub_f32_e32 v62, v62, v223
	v_sub_f32_e32 v63, v63, v223
	v_sub_f32_e32 v64, v64, v223
	v_sub_f32_e32 v65, v65, v223
	v_sub_f32_e32 v34, v34, v223
	v_sub_f32_e32 v35, v35, v223
	v_sub_f32_e32 v36, v36, v223
	v_sub_f32_e32 v37, v37, v223
	v_sub_f32_e32 v38, v38, v223
	v_sub_f32_e32 v39, v39, v223
	v_sub_f32_e32 v40, v40, v223
	v_sub_f32_e32 v41, v41, v223
	v_sub_f32_e32 v42, v42, v223
	v_sub_f32_e32 v43, v43, v223
	v_sub_f32_e32 v44, v44, v223
	v_sub_f32_e32 v45, v45, v223
	v_sub_f32_e32 v46, v46, v223
	v_sub_f32_e32 v47, v47, v223
	v_sub_f32_e32 v48, v48, v223
	v_sub_f32_e32 v49, v49, v223
	v_mov_b32_e32 v246, v224
	v_sub_f32_e32 v230, 0, v224
	v_sub_f32_e32 v231, 0, v224
	v_sub_f32_e32 v232, 0, v224
	v_sub_f32_e32 v233, 0, v224
	v_sub_f32_e32 v234, 0, v224
	v_sub_f32_e32 v235, 0, v224
	v_sub_f32_e32 v236, 0, v224
	v_sub_f32_e32 v237, 0, v224
	v_sub_f32_e32 v238, 0, v224
	v_sub_f32_e32 v239, 0, v224
	v_sub_f32_e32 v240, 0, v224
	v_sub_f32_e32 v241, 0, v224
	v_sub_f32_e32 v242, 0, v224
	v_sub_f32_e32 v243, 0, v224
	v_sub_f32_e32 v244, 0, v224
	v_sub_f32_e32 v245, 0, v224
	v_pk_mul_f32 v[32:33], v[32:33], v[222:223] op_sel_hi:[1,0]
	v_pk_mul_f32 v[30:31], v[30:31], v[222:223] op_sel_hi:[1,0]
	v_pk_mul_f32 v[28:29], v[28:29], v[222:223] op_sel_hi:[1,0]
	v_pk_mul_f32 v[26:27], v[26:27], v[222:223] op_sel_hi:[1,0]
	v_pk_mul_f32 v[24:25], v[24:25], v[222:223] op_sel_hi:[1,0]
	v_pk_mul_f32 v[22:23], v[22:23], v[222:223] op_sel_hi:[1,0]
	v_pk_mul_f32 v[20:21], v[20:21], v[222:223] op_sel_hi:[1,0]
	v_pk_mul_f32 v[18:19], v[18:19], v[222:223] op_sel_hi:[1,0]
	v_pk_mul_f32 v[16:17], v[16:17], v[222:223] op_sel_hi:[1,0]
	v_pk_mul_f32 v[14:15], v[14:15], v[222:223] op_sel_hi:[1,0]
	v_pk_mul_f32 v[12:13], v[12:13], v[222:223] op_sel_hi:[1,0]
	v_pk_mul_f32 v[10:11], v[10:11], v[222:223] op_sel_hi:[1,0]
	v_pk_mul_f32 v[8:9], v[8:9], v[222:223] op_sel_hi:[1,0]
	v_pk_mul_f32 v[6:7], v[6:7], v[222:223] op_sel_hi:[1,0]
	v_pk_mul_f32 v[4:5], v[4:5], v[222:223] op_sel_hi:[1,0]
	v_pk_mul_f32 v[2:3], v[2:3], v[222:223] op_sel_hi:[1,0]
	v_mul_f32_e32 v220, v220, v222
.LBB0_759:
	v_exp_f32_e32 v50, v50
	v_exp_f32_e32 v222, v51
	v_exp_f32_e32 v51, v52
	v_exp_f32_e32 v223, v53
	v_exp_f32_e32 v52, v54
	v_exp_f32_e32 v54, v55
	v_exp_f32_e32 v53, v56
	v_exp_f32_e32 v55, v57
	v_exp_f32_e32 v56, v58
	v_exp_f32_e32 v58, v59
	v_exp_f32_e32 v57, v60
	v_exp_f32_e32 v59, v61
	v_exp_f32_e32 v60, v62
	v_exp_f32_e32 v62, v63
	v_exp_f32_e32 v61, v64
	v_exp_f32_e32 v63, v65
	v_exp_f32_e32 v64, v34
	v_exp_f32_e32 v224, v35
	v_exp_f32_e32 v65, v36
	v_exp_f32_e32 v225, v37
	v_cvt_pk_bf16_f32 v34, v50, v222
	v_cvt_pk_bf16_f32 v35, v51, v223
	v_cvt_pk_bf16_f32 v36, v52, v54
	v_cvt_pk_bf16_f32 v37, v53, v55
	s_waitcnt lgkmcnt(7)
	v_mfma_f32_32x32x16_bf16 v[18:33], v[130:133], v[34:37], v[18:33]
	v_exp_f32_e32 v38, v38
	v_exp_f32_e32 v226, v39
	v_exp_f32_e32 v39, v40
	v_exp_f32_e32 v227, v41
	s_waitcnt lgkmcnt(5)
	v_mfma_f32_32x32x16_bf16 v[2:17], v[126:129], v[34:37], v[2:17]
	v_cvt_pk_bf16_f32 v34, v56, v58
	v_cvt_pk_bf16_f32 v35, v57, v59
	v_cvt_pk_bf16_f32 v36, v60, v62
	v_cvt_pk_bf16_f32 v37, v61, v63
	v_exp_f32_e32 v40, v42
	v_mfma_f32_32x32x16_bf16 v[18:33], v[122:125], v[34:37], v[18:33]
	v_exp_f32_e32 v42, v43
	v_exp_f32_e32 v41, v44
	v_exp_f32_e32 v43, v45
	v_exp_f32_e32 v44, v46
	s_waitcnt lgkmcnt(4)
	v_mfma_f32_32x32x16_bf16 v[2:17], v[118:121], v[34:37], v[2:17]
	v_cvt_pk_bf16_f32 v34, v64, v224
	v_cvt_pk_bf16_f32 v35, v65, v225
	v_cvt_pk_bf16_f32 v36, v38, v226
	v_cvt_pk_bf16_f32 v37, v39, v227
	v_exp_f32_e32 v46, v47
	s_waitcnt lgkmcnt(3)
	v_mfma_f32_32x32x16_bf16 v[18:33], v[114:117], v[34:37], v[18:33]
	v_exp_f32_e32 v45, v48
	v_exp_f32_e32 v47, v49
	v_pk_add_f32 v[48:49], v[50:51], 0 op_sel_hi:[1,0]
	v_pk_add_f32 v[48:49], v[52:53], v[48:49]
	v_pk_add_f32 v[50:51], v[222:223], 0 op_sel_hi:[1,0]
	v_pk_add_f32 v[48:49], v[56:57], v[48:49]
	s_waitcnt lgkmcnt(2)
	v_mfma_f32_32x32x16_bf16 v[2:17], v[110:113], v[34:37], v[2:17]
	v_add_f32_e64 v48, v60, v48
	v_add_f32_e64 v49, v61, v49
	v_add_f32_e64 v50, v54, v50
	v_add_f32_e64 v51, v55, v51
	v_add_f32_e64 v34, v64, v48
	v_add_f32_e64 v35, v65, v49
	v_pk_add_f32 v[50:51], v[58:59], v[50:51]
	v_pk_add_f32 v[38:39], v[38:39], v[34:35]
	v_cvt_pk_bf16_f32 v34, v40, v42
	v_cvt_pk_bf16_f32 v35, v41, v43
	v_cvt_pk_bf16_f32 v36, v44, v46
	v_cvt_pk_bf16_f32 v37, v45, v47
	v_pk_add_f32 v[50:51], v[62:63], v[50:51]
	v_pk_add_f32 v[38:39], v[40:41], v[38:39]
	s_waitcnt lgkmcnt(1)
	v_mfma_f32_32x32x16_bf16 v[18:33], v[106:109], v[34:37], v[18:33]
	v_add_f32_e64 v48, v224, v50
	v_add_f32_e64 v49, v225, v51
	v_add_f32_e64 v38, v44, v38
	v_add_f32_e64 v39, v45, v39
	v_add_f32_e64 v48, v226, v48
	v_add_f32_e64 v49, v227, v49
	v_pk_add_f32 v[40:41], v[42:43], v[48:49]
	s_nop 0
	v_pk_add_f32 v[40:41], v[46:47], v[40:41]
	s_waitcnt lgkmcnt(0)
	v_mfma_f32_32x32x16_bf16 v[2:17], v[102:105], v[34:37], v[2:17]
	v_add_f32_e64 v38, v38, v40
	v_add_f32_e64 v39, v39, v41
	v_add_f32_e32 v1, v38, v39
	v_add_f32_e32 v220, v220, v1
